# on top of v60: the epilogue-alignment barrier of the leading half moved below the epilogue's input-load issue in the ROPE and RES GEMMs (loads fly while it waits for the trailing half's last MFMA bloc
# baseline (speedup 1.0000x reference)
.Lpeel_exit_r:
.LBB0_224:
	s_lshl_b32 s50, s8, 8
	s_add_i32 s50, s50, s71
	v_or_b32_e32 v214, s50, v197
	v_ashrrev_i32_e32 v215, 31, v214
	v_or_b32_e32 v210, 16, v214
	v_or_b32_e32 v206, 32, v214
	v_lshlrev_b64 v[216:217], 6, v[214:215]
	v_ashrrev_i32_e32 v211, 31, v210
	v_ashrrev_i32_e32 v207, 31, v206
	v_or_b32_e32 v202, 48, v214
	v_add_u32_e32 v186, 0x80, v214
	v_lshl_add_u64 v[50:51], v[174:175], 0, v[216:217]
	v_lshlrev_b64 v[212:213], 6, v[210:211]
	v_lshlrev_b64 v[208:209], 6, v[206:207]
	v_ashrrev_i32_e32 v203, 31, v202
	v_ashrrev_i32_e32 v187, 31, v186
	v_lshl_add_u64 v[52:53], v[174:175], 0, v[212:213]
	global_load_dwordx4 v[218:221], v[50:51], off
	global_load_dwordx4 v[244:247], v[52:53], off
	v_lshl_add_u64 v[50:51], v[174:175], 0, v[208:209]
	v_lshlrev_b64 v[204:205], 6, v[202:203]
	v_lshlrev_b64 v[188:189], 6, v[186:187]
	v_add_u32_e32 v184, 0x90, v214
	v_lshl_add_u64 v[52:53], v[174:175], 0, v[204:205]
	global_load_dwordx4 v[248:251], v[50:51], off
	global_load_dwordx4 v[234:237], v[52:53], off
	v_lshl_add_u64 v[50:51], v[174:175], 0, v[188:189]
	v_ashrrev_i32_e32 v185, 31, v184
	global_load_dwordx4 v[158:161], v[50:51], off
	v_add_u32_e32 v182, 0xa0, v214
	v_lshlrev_b64 v[50:51], 6, v[184:185]
	v_lshl_add_u64 v[50:51], v[174:175], 0, v[50:51]
	v_ashrrev_i32_e32 v183, 31, v182
	v_add_u32_e32 v180, 0xb0, v214
	global_load_dwordx4 v[150:153], v[50:51], off
	v_lshlrev_b64 v[50:51], 6, v[182:183]
	v_lshl_add_u64 v[50:51], v[174:175], 0, v[50:51]
	v_ashrrev_i32_e32 v181, 31, v180
	global_load_dwordx4 v[146:149], v[50:51], off
	v_lshlrev_b64 v[50:51], 6, v[180:181]
	v_lshl_add_u64 v[50:51], v[174:175], 0, v[50:51]
	global_load_dwordx4 v[154:157], v[50:51], off
	s_ashr_i32 s8, s8, 5
	s_mul_hi_i32 s9, s8, s48
	s_mul_i32 s8, s8, s48
	s_lshl_b64 s[8:9], s[8:9], 2
	s_add_u32 s10, s36, s8
	s_addc_u32 s11, s37, s9
	s_lshl_b32 s8, s44, 8
	s_ashr_i32 s9, s8, 31
	s_lshl_b64 s[8:9], s[8:9], 2
	s_add_u32 s8, s10, s8
	s_addc_u32 s9, s11, s9
	global_load_dwordx4 v[66:69], v242, s[8:9] offset:16
	global_load_dwordx4 v[70:73], v242, s[8:9]
	global_load_dwordx4 v[50:53], v242, s[8:9] offset:528
	global_load_dwordx4 v[54:57], v242, s[8:9] offset:512
	v_and_b32_e32 v203, 64, v227
	v_xor_b32_e32 v187, 16, v227
	v_add_u32_e32 v203, 64, v203
	v_xor_b32_e32 v207, 32, v227
	v_cmp_lt_i32_e32 vcc, v187, v203
	s_cmp_lt_i32 s44, 6
	s_cselect_b64 s[10:11], -1, 0
	v_cndmask_b32_e32 v187, v227, v187, vcc
	v_cmp_lt_i32_e32 vcc, v207, v203
	v_lshlrev_b32_e32 v187, 2, v187
	s_and_b64 s[46:47], s[14:15], s[10:11]
	v_cndmask_b32_e32 v203, v227, v207, vcc
	v_lshlrev_b32_e32 v207, 2, v203
	s_and_b64 s[42:43], s[46:47], s[4:5]
	s_and_b64 vcc, exec, s[12:13]
	s_cbranch_vccz .Lepi_nobar_r
	s_barrier
.Lepi_nobar_r:
	s_waitcnt vmcnt(0)
	v_add_f32_e32 v203, v218, v219
	v_add_f32_e32 v211, v220, v221
	v_add_f32_e32 v203, v203, v211
	v_add_f32_e32 v211, v244, v245
	v_add_f32_e32 v215, v246, v247
	v_add_f32_e32 v218, v248, v249
	v_add_f32_e32 v219, v250, v251
	v_add_f32_e32 v220, v234, v235
	v_add_f32_e32 v221, v236, v237
	v_add_f32_e32 v158, v158, v159
	v_add_f32_e32 v159, v160, v161
	v_add_f32_e32 v161, v211, v215
	v_add_f32_e32 v211, v218, v219
	v_add_f32_e32 v215, v220, v221
	v_add_f32_e32 v158, v158, v159
	v_add_f32_e32 v150, v150, v151
	v_add_f32_e32 v151, v152, v153
	v_add_f32_e32 v150, v150, v151
	ds_bpermute_b32 v160, v187, v203
	v_add_f32_e32 v146, v146, v147
	v_add_f32_e32 v147, v148, v149
	v_add_f32_e32 v146, v146, v147
	v_add_f32_e32 v148, v154, v155
	v_add_f32_e32 v149, v156, v157
	v_add_f32_e32 v148, v148, v149
	ds_bpermute_b32 v159, v187, v161
	ds_bpermute_b32 v220, v187, v211
	ds_bpermute_b32 v221, v187, v215
	ds_bpermute_b32 v222, v187, v158
	ds_bpermute_b32 v151, v187, v150
	ds_bpermute_b32 v147, v187, v146
	ds_bpermute_b32 v149, v187, v148
	s_waitcnt lgkmcnt(7)
	v_add_f32_e32 v218, v203, v160
	s_waitcnt lgkmcnt(6)
	v_add_f32_e32 v251, v161, v159
	s_waitcnt lgkmcnt(5)
	v_add_f32_e32 v249, v211, v220
	s_waitcnt lgkmcnt(4)
	v_add_f32_e32 v247, v215, v221
	s_waitcnt lgkmcnt(3)
	v_add_f32_e32 v245, v158, v222
	s_waitcnt lgkmcnt(2)
	v_add_f32_e32 v243, v150, v151
	s_waitcnt lgkmcnt(1)
	v_add_f32_e32 v211, v146, v147
	s_waitcnt lgkmcnt(0)
	v_add_f32_e32 v203, v148, v149
	ds_bpermute_b32 v219, v207, v218
	ds_bpermute_b32 v252, v207, v251
	ds_bpermute_b32 v250, v207, v249
	ds_bpermute_b32 v248, v207, v247
	ds_bpermute_b32 v246, v207, v245
	ds_bpermute_b32 v244, v207, v243
	ds_bpermute_b32 v215, v207, v211
	ds_bpermute_b32 v207, v207, v203
	v_mov_b32_e32 v158, 0
	v_mov_b32_e32 v150, 1.0
	v_mov_b32_e32 v151, 1.0
	v_mov_b32_e32 v152, 1.0
	v_mov_b32_e32 v153, 1.0
	v_mov_b32_e32 v146, 1.0
	v_mov_b32_e32 v147, 1.0
	v_mov_b32_e32 v148, 1.0
	v_mov_b32_e32 v149, 1.0
	v_mov_b32_e32 v159, 0
	v_mov_b32_e32 v160, 0
	v_mov_b32_e32 v161, 0
	v_mov_b32_e32 v156, 0
	v_mov_b32_e32 v157, 0
	v_mov_b32_e32 v154, 0
	v_mov_b32_e32 v155, 0
	s_and_saveexec_b64 s[8:9], s[42:43]
	s_cbranch_execz .LBB0_226
	v_and_b32_e32 v146, 0x3fc0, v216
	v_add_u32_e32 v146, 0x21000, v146
	ds_read_b128 v[154:157], v146 offset:32
	ds_read_b128 v[220:223], v146 offset:48
	ds_read_b128 v[150:153], v146
	s_nop 0
	ds_read_b128 v[146:149], v146 offset:16
	s_waitcnt lgkmcnt(3)
	v_pk_mul_f32 v[160:161], v[172:173], v[156:157]
	v_pk_mul_f32 v[158:159], v[170:171], v[154:155]
	s_waitcnt lgkmcnt(2)
	v_pk_mul_f32 v[154:155], v[172:173], v[222:223]
	v_pk_mul_f32 v[156:157], v[170:171], v[220:221]

.Lpeel_exit_s:
.LBB0_312:
	s_lshl_b32 s46, s24, 2
	s_lshl_b32 s10, s42, 5
	s_or_b32 s8, s46, s70
	s_and_b32 s10, s10, 0xfffffc00
	s_ashr_i32 s9, s8, 31
	s_ashr_i32 s11, s10, 31
	s_ashr_i32 s43, s42, 31
	s_lshl_b64 s[8:9], s[8:9], 14
	s_lshl_b64 s[50:51], s[10:11], 2
	v_lshl_or_b32 v210, s24, 8, v220
	s_add_u32 s10, s72, s50
	s_addc_u32 s11, s73, s51
	v_ashrrev_i32_e32 v211, 31, v210
	s_add_u32 s48, s82, s50
	v_lshlrev_b64 v[50:51], 2, v[210:211]
	s_addc_u32 s49, s83, s51
	v_lshl_add_u64 v[52:53], s[10:11], 0, v[50:51]
	s_lshl_b64 s[10:11], s[42:43], 18
	s_add_u32 s8, s8, s10
	s_addc_u32 s9, s9, s11
	v_lshl_add_u64 v[212:213], s[8:9], 0, v[208:209]
	v_lshl_add_u64 v[214:215], v[212:213], 1, s[74:75]
	s_movk_i32 s8, 0x1000
	v_add_co_u32_e32 v154, vcc, s8, v214
	v_lshl_add_u64 v[58:59], s[48:49], 0, v[50:51]
	s_nop 0
	v_addc_co_u32_e32 v155, vcc, 0, v215, vcc
	global_load_dwordx4 v[90:93], v[52:53], off offset:16
	global_load_dwordx4 v[94:97], v[52:53], off
	global_load_dwordx4 v[82:85], v[58:59], off offset:16
	global_load_dwordx4 v[86:89], v[58:59], off
	global_load_dwordx4 v[66:69], v[52:53], off offset:144
	global_load_dwordx4 v[70:73], v[52:53], off offset:128
	s_nop 0
	global_load_dwordx4 v[50:53], v[58:59], off offset:144
	s_nop 0
	global_load_dwordx4 v[58:61], v[58:59], off offset:128
	s_nop 0
	global_load_dwordx4 v[216:219], v[214:215], off
	global_load_dwordx4 v[186:189], v[214:215], off offset:2048
	global_load_dwordx4 v[182:185], v[154:155], off
	global_load_dwordx4 v[178:181], v[154:155], off offset:2048
	global_load_dwordx4 v[174:177], v[214:215], off offset:64
	global_load_dwordx4 v[170:173], v[214:215], off offset:2112
	global_load_dwordx4 v[158:161], v[154:155], off offset:64
	s_nop 0
	global_load_dwordx4 v[154:157], v[154:155], off offset:2112
	s_and_b64 vcc, exec, s[18:19]
	s_cbranch_vccz .Lepi_nobar_s
	s_barrier
.Lepi_nobar_s:
	s_andn2_b64 vcc, exec, s[26:27]
	s_waitcnt vmcnt(0)
	v_lshlrev_b32_e32 v222, 16, v216
	v_and_b32_e32 v223, 0xffff0000, v216
	v_lshlrev_b32_e32 v216, 16, v217
	v_and_b32_e32 v217, 0xffff0000, v217
	v_lshlrev_b32_e32 v234, 16, v218
	v_and_b32_e32 v235, 0xffff0000, v218
	v_lshlrev_b32_e32 v218, 16, v219
	v_and_b32_e32 v219, 0xffff0000, v219
	v_pk_fma_f32 v[168:169], v[168:169], v[96:97], v[216:217]
	v_pk_fma_f32 v[166:167], v[166:167], v[94:95], v[222:223]
	v_pk_fma_f32 v[164:165], v[164:165], v[92:93], v[218:219]
	v_cvt_pk_bf16_f32 v216, v166, v167
	v_pk_fma_f32 v[162:163], v[162:163], v[90:91], v[234:235]
	v_cvt_pk_bf16_f32 v217, v168, v169
	s_nop 0
	v_cvt_pk_bf16_f32 v218, v162, v163
	v_cvt_pk_bf16_f32 v219, v164, v165
	global_store_dwordx4 v[214:215], v[216:219], off
	s_nop 1
	v_cndmask_b32_e64 v216, 0, 1, s[26:27]
	v_cmp_ne_u32_e64 s[8:9], 1, v216
	s_cbranch_vccnz .LBB0_314
	v_pk_mul_f32 v[218:219], v[88:89], v[168:169]
	v_pk_mul_f32 v[216:217], v[86:87], v[166:167]
	v_pk_mul_f32 v[222:223], v[84:85], v[164:165]
	v_pk_mul_f32 v[234:235], v[82:83], v[162:163]
	v_cvt_pk_bf16_f32 v216, v216, v217
	v_cvt_pk_bf16_f32 v217, v218, v219
	s_nop 0
	v_cvt_pk_bf16_f32 v218, v234, v235
	v_cvt_pk_bf16_f32 v219, v222, v223
	v_lshl_add_u64 v[222:223], v[212:213], 1, s[58:59]
	global_store_dwordx4 v[222:223], v[216:219], off
